# DF loop: the early half (which has slack) stages the late half's K/V pieces too; the late half issues no LDS-DMA inside the loop
# baseline (speedup 1.0000x reference)
.LBB0_397:
	s_andn2_b64 vcc, exec, s[8:9]
	s_cbranch_vccnz .LBB0_399
	s_waitcnt vmcnt(0) lgkmcnt(0)
	s_barrier

.LBB0_402:
	s_and_b32 s8, s26, 8
	s_add_i32 s8, s8, 0
	s_add_i32 s8, s8, 0x241c0
	v_mov_b32_e32 v0, s8
	ds_read_b64 v[14:15], v0
	s_cmp_lt_i32 s12, 3
.LBB0_404:
	s_mov_b32 s97, s96
	s_waitcnt lgkmcnt(0)
	v_cmp_eq_u64_e32 vcc, s[96:97], v[14:15]
	s_nop 1
	v_cndmask_b32_e64 v0, 0, 1, vcc
	s_nop 0
	v_readfirstlane_b32 s8, v0
	s_bitcmp1_b32 s8, 0
	s_cselect_b64 s[8:9], -1, 0
	s_and_b64 vcc, exec, s[8:9]
	s_cbranch_vccnz .LBB0_420
	s_cmp_gt_i32 s12, s21
	s_cbranch_scc1 .LBB0_417
	s_xor_b64 s[12:13], s[10:11], -1
	s_add_i32 s10, s27, 0xffff4000
	s_and_b32 s10, s10, 0xc000
	s_add_i32 s14, s34, s10
	v_add_u32_e32 v0, s14, v222
	s_mov_b64 s[10:11], -1
	s_and_b64 vcc, exec, s[12:13]
	v_add_u32_e32 v202, v0, v223
	v_add_u32_e32 v15, v0, v224
	v_add_u32_e32 v14, v0, v225
	v_add_u32_e32 v0, v0, v233
	s_cbranch_vccz .LBB0_408
	ds_read_b128 v[80:83], v202
	ds_read_b128 v[84:87], v202 offset:4096
	ds_read_b128 v[148:151], v15
	ds_read_b128 v[204:207], v15 offset:4096
	ds_read_b128 v[208:211], v14
	ds_read_b128 v[212:215], v14 offset:4096
	ds_read_b128 v[238:241], v0
	ds_read_b128 v[242:245], v0 offset:4096
	s_waitcnt lgkmcnt(7)
	v_mfma_f32_32x32x16_bf16 v[96:111], v[80:83], v[136:139], 0
	s_mov_b64 s[10:11], 0
	s_waitcnt lgkmcnt(6)
	v_mfma_f32_32x32x16_bf16 v[80:95], v[84:87], v[136:139], 0
	s_waitcnt lgkmcnt(5)
	v_mfma_f32_32x32x16_bf16 v[96:111], v[148:151], v[128:131], v[96:111]
	s_waitcnt lgkmcnt(4)
	v_mfma_f32_32x32x16_bf16 v[80:95], v[204:207], v[128:131], v[80:95]
	s_waitcnt lgkmcnt(3)
	v_mfma_f32_32x32x16_bf16 v[96:111], v[208:211], v[140:143], v[96:111]
	s_waitcnt lgkmcnt(2)
	v_mfma_f32_32x32x16_bf16 v[80:95], v[212:215], v[140:143], v[80:95]
	s_waitcnt lgkmcnt(1)
	v_mfma_f32_32x32x16_bf16 v[96:111], v[238:241], v[132:135], v[96:111]
	s_waitcnt lgkmcnt(0)
	v_mfma_f32_32x32x16_bf16 v[80:95], v[242:245], v[132:135], v[80:95]

.LBB0_435:
	s_add_i32 s23, s22, 8
	s_and_b32 s8, s23, 8
	s_add_i32 s8, s8, 0
	s_add_i32 s8, s8, 0x241c0
	v_mov_b32_e32 v0, s8
	ds_read_b64 v[2:3], v0
	s_cmp_lt_i32 s15, 3
	s_cbranch_scc1 .LBB0_437
	s_mov_b64 s[90:91], 0x2000
	s_and_b32 s11, s13, 0xc000
	s_cmp_gt_i32 s14, 1
	s_cselect_b32 s8, -2, 3
	s_add_i32 s8, s8, s14
	s_add_i32 s80, s10, -4
	s_lshl_b32 s24, s8, 14
	s_lshl_b64 s[8:9], s[80:81], 14
	v_lshl_add_u64 v[4:5], v[180:181], 0, s[8:9]
	s_add_i32 s11, s76, s11
	s_mov_b32 s25, m0
	s_mov_b32 m0, s11
	s_nop 0
	global_load_lds_dwordx4 v[4:5], off
	s_mov_b32 m0, s25
	v_lshl_add_u64 v[240:241], v[4:5], 0, s[90:91]
	s_add_i32 s92, s11, 0x1000
	s_mov_b32 m0, s92
	s_nop 0
	global_load_lds_dwordx4 v[240:241], off
	s_mov_b32 m0, s25
	v_lshl_add_u64 v[4:5], v[4:5], 0, s[88:89]
	s_addk_i32 s11, 0x2000
	s_mov_b32 s25, m0
	s_mov_b32 m0, s11
	s_nop 0
	global_load_lds_dwordx4 v[4:5], off
	s_mov_b32 m0, s25
	v_lshl_add_u64 v[240:241], v[4:5], 0, s[90:91]
	s_add_i32 s92, s11, 0x1000
	s_mov_b32 m0, s92
	s_nop 0
	global_load_lds_dwordx4 v[240:241], off
	s_mov_b32 m0, s25
	v_lshl_add_u64 v[4:5], v[182:183], 0, s[8:9]
	s_add_i32 s8, s31, s24
	s_mov_b32 s9, m0
	s_mov_b32 m0, s8
	s_nop 0
	global_load_lds_dwordx4 v[4:5], off
	s_mov_b32 m0, s9
	v_lshl_add_u64 v[240:241], v[4:5], 0, 64
	s_add_i32 s92, s8, 0x1000
	s_mov_b32 m0, s92
	s_nop 0
	global_load_lds_dwordx4 v[240:241], off
	s_mov_b32 m0, s9
	v_lshl_add_u64 v[4:5], v[4:5], 0, s[88:89]
	s_addk_i32 s8, 0x2000
	s_mov_b32 s9, m0
	s_mov_b32 m0, s8
	s_nop 0
	global_load_lds_dwordx4 v[4:5], off
	s_mov_b32 m0, s9
	v_lshl_add_u64 v[240:241], v[4:5], 0, 64
	s_add_i32 s92, s8, 0x1000
	s_mov_b32 m0, s92
	s_nop 0
	global_load_lds_dwordx4 v[240:241], off
	s_mov_b32 m0, s9
